# v19 + code placement: one s_nop pad at four phase starts so every GEMM K-loop head sits at 0 mod 8 bytes
# speedup vs baseline: 1.0057x; 1.0057x over previous
; #define LAS __attribute__((address_space(3)))
;     __device__ bool next(int i, Unit& u) const {
;         const long L = (long)i * G + c; if (L >= nwg) return false;
;         int wgid = (int)L; { const int q = nwg / NXCD, r = nwg % NXCD, xcd = wgid % NXCD, off = wgid / NXCD; wgid = (xcd < r ? xcd * (q + 1) : r * (q + 1) + (xcd - r) * q) + off; }
;         const int nig = WGM * nN, gid = wgid / nig, fm = gid * WGM, gsz = (nM - fm) < WGM ? (nM - fm) : WGM;
;         u.pm = fm + ((wgid % nig) % gsz); u.pn = (wgid % nig) / gsz; return true;
;     }
; template <class Epi, bool ALIGN_EPI = false, bool SP2 = true>
; __device__ __forceinline__ void gemm_phase(LAS unsigned char* lds, const Gemm g, const StaticOrder& S, const Epi& E) {
;     const int tid = threadIdx.x, wid = __builtin_amdgcn_readfirstlane(tid >> 6), lane = tid & 63, wr = wid >> 2, wc = wid & 3, fr = lane & 15, fq = lane >> 4;
;     const int K = g.K, nt = K / BK;
;     unsigned voffA[2], voffB[2];
; #pragma unroll
;     for (int i = 0; i < 2; ++i) { int R, C; stage_rc(tid * 16 + i * 8192, R, C); const int Rb = (R & ~31) + perm32(R & 31);
;         voffA[i] = (unsigned)(R * K + C) * 2u; voffB[i] = (unsigned)(Rb * K + C) * 2u; }
; __global__ void __launch_bounds__(NTHREADS, 2) mk_fwd(Params P) {
;     ...
;     if (IN(3)) {
;         { pg8::Gemm g{PB, WP, 2 * MTOK, 2048, 256, 32, 8}; pg8::StaticOrder S; S.init(2 * MTOK, 2048, G, bid);
.LBB0_291:
	s_nop 0
	s_cmp_lt_i32 s42, 4
	s_cselect_b64 s[4:5], -1, 0
	s_and_b64 s[16:17], s[4:5], s[0:1]
	s_andn2_b64 vcc, exec, s[16:17]
	s_cbranch_vccnz .LBB0_366
	s_waitcnt vmcnt(0)
	v_lshlrev_b32_e32 v0, 4, v164
	v_and_b32_e32 v1, 32, v164
	v_bitop3_b32 v56, v0, v1, 48 bitop3:0x6c
	v_lshrrev_b32_e32 v1, 5, v164
	v_lshrrev_b32_e32 v3, 1, v164
	v_and_b32_e32 v1, 4, v1
	v_bfe_u32 v2, v164, 2, 2
	v_and_b32_e32 v148, 24, v3
	v_bfe_u32 v58, v164, 2, 4
	v_or3_b32 v1, v1, v2, v148
	v_lshrrev_b32_e32 v2, 3, v164
	s_movk_i32 s0, 0x70
	v_and_or_b32 v63, v2, s0, v58
	s_movk_i32 s0, 0x60
	v_add_u32_e32 v59, 0x2000, v0
	v_and_or_b32 v64, v2, s0, v1
	v_lshrrev_b32_e32 v0, 7, v59
	s_movk_i32 s0, 0xf0
	v_and_or_b32 v65, v0, s0, v58
	s_movk_i32 s0, 0xe0
	v_and_or_b32 v66, v0, s0, v1
	v_lshlrev_b32_e32 v0, 6, v164
	v_and_b32_e32 v57, 64, v164
	v_and_b32_e32 v60, 0x3c0, v0
	v_lshlrev_b32_e32 v0, 2, v164
	v_readfirstlane_b32 s68, v164
	v_or_b32_e32 v62, v56, v57
	v_and_b32_e32 v149, 15, v164
	s_cmpk_gt_i32 s2, 0x1ff
	v_and_b32_e32 v61, 32, v0
	s_cbranch_scc1 .LBB0_310
	s_ashr_i32 s3, s2, 31
	s_lshr_b32 s0, s3, 29
	s_add_i32 s4, s2, s0
	s_and_b32 s0, s4, -8
	s_sub_i32 s6, s2, s0
	s_cmp_gt_i32 s6, -1
	s_cbranch_scc0 .LBB0_295
	s_lshl_b32 s5, s6, 6
	s_cbranch_execz .LBB0_296
	s_branch .LBB0_297

; __global__ void __launch_bounds__(NTHREADS, 2) mk_fwd(Params P) {
;     ...
;     if (IN(5)) {
;         transpose_convert(lds, P.w_in_b, WINB, 2048, 8192, G, bid);
;         pg8::Gemm g{X1B, WG0, MTOK, 2048, 2048, 1 << 30, 0}; pg8::StaticOrder S; S.init(MTOK, 2048, G, bid);
.LBB0_416:
	s_nop 0
	s_cmp_lt_i32 s42, 6
	s_cselect_b64 s[0:1], -1, 0
	s_cmp_gt_i32 s43, 5
	s_setprio 0
	s_cselect_b64 s[4:5], -1, 0
	s_and_b64 s[0:1], s[0:1], s[4:5]
	s_andn2_b64 vcc, exec, s[0:1]
	s_cbranch_vccnz .LBB0_448
	v_and_b32_e32 v20, 15, v164
	v_mov_b32_e32 v46, 0x20008
	ds_read_b32 v48, v46
	s_waitcnt lgkmcnt(0)
	v_readfirstlane_b32 s99, v48
	s_and_b32 s99, s99, 0xff
	s_lshr_b32 s3, s99, 5
	s_and_b32 s4, s99, 31
	s_mov_b32 s100, 11
	s_mov_b32 s5, 0
	s_cmp_lt_u32 s3, 1
	s_cbranch_scc1 .Lrk5_done
	s_mov_b32 s100, 10
	s_movk_i32 s5, 352
	s_cmp_lt_u32 s3, 2
	s_cbranch_scc1 .Lrk5_done
	s_mov_b32 s100, 9
	s_movk_i32 s5, 672
	s_cmp_lt_u32 s3, 3
	s_cbranch_scc1 .Lrk5_done
	s_mov_b32 s100, 9
	s_movk_i32 s5, 960
	s_cmp_lt_u32 s3, 4
	s_cbranch_scc1 .Lrk5_done
	s_mov_b32 s100, 8
	s_movk_i32 s5, 1248
	s_cmp_lt_u32 s3, 5
	s_cbranch_scc1 .Lrk5_done
	s_mov_b32 s100, 7
	s_movk_i32 s5, 1504
	s_cmp_lt_u32 s3, 6
	s_cbranch_scc1 .Lrk5_done
	s_mov_b32 s100, 6
	s_movk_i32 s5, 1728
	s_cmp_lt_u32 s3, 7
	s_cbranch_scc1 .Lrk5_done
	s_mov_b32 s100, 4
	s_movk_i32 s5, 1920

;     __device__ bool next(int i, Unit& u) const {
;         const long L = (long)i * G + c; if (L >= nwg) return false;
;         int wgid = (int)L; { const int q = nwg / NXCD, r = nwg % NXCD, xcd = wgid % NXCD, off = wgid / NXCD; wgid = (xcd < r ? xcd * (q + 1) : r * (q + 1) + (xcd - r) * q) + off; }
; __global__ void __launch_bounds__(NTHREADS, 2) mk_fwd(Params P) {
;     ...
;     if (IN(6)) {
;         pg8::Gemm g{SLOTA, WINB, MTOK, 8192, 2048, 1 << 30, 0}; pg8::StaticOrder S; S.init(MTOK, 8192, G, bid);
;         EpiL1In E{Qb, Kb, VTb, Zb, KPART}; pg8::gemm_phase<EpiL1In, true>(lds, g, S, E);
.LBB0_498:
	s_nop 0
	v_mov_b32_e32 v251, 0xa140
	global_load_dword v250, v251, s[54:55] sc1
	s_add_u32 s3, s40, 0x3c00000
	s_addc_u32 s76, s41, 0
	s_add_u32 s0, s40, 0xa000000
	s_addc_u32 s1, s41, 0
	s_cmp_lt_i32 s42, 7
	s_cselect_b64 s[6:7], -1, 0
	s_and_b64 s[16:17], s[6:7], s[4:5]
	s_andn2_b64 vcc, exec, s[16:17]
	s_cbranch_vccnz .LBB0_571
	s_cmpk_lt_i32 s2, 0x400
	s_cselect_b64 s[4:5], -1, 0
	s_cmpk_gt_i32 s2, 0x3ff
	v_readfirstlane_b32 s26, v164
	s_cbranch_scc1 .LBB0_505
	s_ashr_i32 s6, s2, 31
	s_lshr_b32 s6, s6, 29
	s_add_i32 s8, s2, s6
	s_and_b32 s6, s8, -8
	s_sub_i32 s9, s2, s6
	s_cmp_gt_i32 s9, -1
	s_cbranch_scc0 .LBB0_502
	s_lshl_b32 s10, s9, 7
	s_cbranch_execz .LBB0_503
	s_branch .LBB0_504

;     __device__ bool next(int i, Unit& u) const {
;         const long L = (long)i * G + c; if (L >= nwg) return false;
;         int wgid = (int)L; { const int q = nwg / NXCD, r = nwg % NXCD, xcd = wgid % NXCD, off = wgid / NXCD; wgid = (xcd < r ? xcd * (q + 1) : r * (q + 1) + (xcd - r) * q) + off; }
; __global__ void __launch_bounds__(NTHREADS, 2) mk_fwd(Params P) {
;     ...
;     if (IN(10)) {
;         pg8::Gemm g{X3B, WG1, MTOK, 2048, 2048, 1 << 30, 0}; pg8::StaticOrder S; S.init(MTOK, 2048, G, bid);
.LBB0_837:
	s_nop 0
	s_cmp_lt_i32 s42, 11
	s_cselect_b64 s[0:1], -1, 0
	s_cmp_gt_i32 s43, 10
	s_setprio 0
	s_cselect_b64 s[4:5], -1, 0
	s_and_b64 s[0:1], s[0:1], s[4:5]
	s_andn2_b64 vcc, exec, s[0:1]
	s_cbranch_vccnz .LBB0_862
	s_cmpk_gt_i32 s2, 0xff
	v_readfirstlane_b32 s10, v164
	s_cbranch_scc1 .LBB0_862
	s_ashr_i32 s3, s2, 31
	s_lshr_b32 s0, s3, 29
	s_add_i32 s6, s2, s0
	s_and_b32 s0, s6, -8
	s_sub_i32 s5, s2, s0
	s_cmp_gt_i32 s5, -1
	s_cbranch_scc0 .LBB0_841
	s_lshl_b32 s4, s5, 5
	s_ashr_i32 s0, s6, 3
	s_cbranch_execz .LBB0_842
	s_branch .LBB0_843
